# v111 + RNN YA output rows stored write-through (sc1) instead of nt
# speedup vs baseline: 1.0148x; 1.0029x over previous
.LBB0_529:
	s_max_i32 s12, s76, 1
	s_add_i32 s28, s12, -1
	s_cmp_lt_i32 s24, s76
	s_cselect_b64 vcc, -1, 0
	s_and_b64 s[12:13], vcc, exec
	s_cselect_b32 s12, s24, s28
	s_add_i32 s12, s12, s66
	s_ashr_i32 s13, s12, 31
	s_lshl_b64 s[12:13], s[12:13], 13
	s_add_i32 s16, s24, 1
	s_cmp_lt_i32 s16, s76
	v_lshl_add_u64 v[0:1], v[76:77], 0, s[12:13]
	s_cselect_b64 s[12:13], -1, 0
	s_and_b64 s[14:15], s[12:13], exec
	s_cselect_b32 s14, s16, s28
	s_add_i32 s14, s14, s66
	s_ashr_i32 s15, s14, 31
	s_lshl_b64 s[14:15], s[14:15], 13
	s_add_i32 s18, s24, 2
	s_cmp_lt_i32 s18, s76
	s_waitcnt lgkmcnt(0)
	s_barrier
	global_load_dwordx2 v[14:15], v[0:1], off sc1
	v_lshl_add_u64 v[0:1], v[76:77], 0, s[14:15]
	s_cselect_b64 s[14:15], -1, 0
	s_and_b64 s[16:17], s[14:15], exec
	s_cselect_b32 s16, s18, s28
	s_add_i32 s16, s16, s66
	s_ashr_i32 s17, s16, 31
	s_lshl_b64 s[16:17], s[16:17], 13
	s_add_i32 s20, s24, 3
	s_cmp_lt_i32 s20, s76
	global_load_dwordx2 v[12:13], v[0:1], off sc1
	v_lshl_add_u64 v[0:1], v[76:77], 0, s[16:17]
	s_cselect_b64 s[16:17], -1, 0
	s_and_b64 s[18:19], s[16:17], exec
	s_cselect_b32 s18, s20, s28
	s_add_i32 s18, s18, s66
	s_ashr_i32 s19, s18, 31
	s_lshl_b64 s[18:19], s[18:19], 13
	s_add_i32 s22, s24, 4
	s_cmp_lt_i32 s22, s76
	global_load_dwordx2 v[80:81], v[0:1], off sc1
	v_lshl_add_u64 v[0:1], v[76:77], 0, s[18:19]
	s_cselect_b64 s[18:19], -1, 0
	s_and_b64 s[20:21], s[18:19], exec
	s_cselect_b32 s20, s22, s28
	s_add_i32 s20, s20, s66
	s_ashr_i32 s21, s20, 31
	s_lshl_b64 s[20:21], s[20:21], 13
	s_add_i32 s25, s24, 5
	s_cmp_lt_i32 s25, s76
	global_load_dwordx2 v[82:83], v[0:1], off sc1
	v_lshl_add_u64 v[0:1], v[76:77], 0, s[20:21]
	s_cselect_b64 s[20:21], -1, 0
	s_and_b64 s[22:23], s[20:21], exec
	s_cselect_b32 s22, s25, s28
	s_add_i32 s22, s22, s66
	s_ashr_i32 s23, s22, 31
	s_lshl_b64 s[22:23], s[22:23], 13
	s_add_i32 s25, s24, 6
	s_cmp_lt_i32 s25, s76
	global_load_dwordx2 v[84:85], v[0:1], off sc1
	v_lshl_add_u64 v[0:1], v[76:77], 0, s[22:23]
	s_cselect_b64 s[22:23], -1, 0
	s_and_b64 s[26:27], s[22:23], exec
	s_cselect_b32 s25, s25, s28
	s_add_i32 s26, s25, s66
	s_ashr_i32 s27, s26, 31
	s_lshl_b64 s[26:27], s[26:27], 13
	s_add_i32 s29, s24, 7
	s_cmp_lt_i32 s29, s76
	s_cselect_b64 s[24:25], -1, 0
	global_load_dwordx2 v[86:87], v[0:1], off sc1
	v_lshl_add_u64 v[0:1], v[76:77], 0, s[26:27]
	s_and_b64 s[26:27], s[24:25], exec
	s_cselect_b32 s26, s29, s28
	s_add_i32 s26, s26, s66
	s_ashr_i32 s27, s26, 31
	global_load_dwordx2 v[88:89], v[0:1], off sc1
	s_lshl_b64 s[26:27], s[26:27], 13
	v_lshl_add_u64 v[0:1], v[76:77], 0, s[26:27]
	global_load_dwordx2 v[90:91], v[0:1], off sc1
	v_lshlrev_b32_e32 v226, 16, v211
	v_and_b32_e32 v211, 0xffff0000, v211
	v_mov_b32_e32 v1, v209
	v_mov_b32_e32 v2, v209
	v_add_f32_e32 v3, v225, v226
	v_lshlrev_b32_e32 v227, 16, v210
	v_permlane16_swap_b32_e32 v1, v2
	v_fma_f32 v3, v156, v3, v211
	v_and_b32_e32 v228, 0xffff0000, v210
	v_cndmask_b32_e64 v225, v1, v2, s[4:5]
	v_fma_f32 v1, v155, v3, v227
	v_fma_f32 v230, v154, v1, v228
	v_mov_b32_e32 v1, v230
	v_mov_b32_e32 v2, v230
	s_nop 1
	v_permlane16_swap_b32_e32 v1, v2
	v_mov_b32_e32 v0, v60
	v_cndmask_b32_e64 v231, v1, v2, s[4:5]
	s_waitcnt vmcnt(7)
	v_fmac_f32_e32 v15, v113, v14
	v_cndmask_b32_e32 v14, v113, v15, vcc
	v_mul_f32_e32 v229, v209, v225
	v_fma_f32 v232, v230, v225, v231
	v_fmac_f32_e32 v230, v209, v231
	v_mov_b32_e32 v15, v229
	v_lshlrev_b32_e32 v1, 3, v0
	v_ashrrev_i32_e32 v209, 4, v0
	v_and_b32_e32 v210, 0x78, v1
	s_waitcnt vmcnt(6)
	v_fmac_f32_e32 v13, v14, v12
	v_cndmask_b32_e64 v12, v14, v13, s[12:13]
	v_add_u32_e32 v0, s77, v209
	v_or_b32_e32 v2, s37, v210
	v_ashrrev_i32_e32 v1, 31, v0
	v_lshlrev_b32_e32 v66, 1, v2
	v_lshlrev_b64 v[10:11], 11, v[0:1]
	v_mov_b32_e32 v14, v229
	v_lshl_add_u64 v[0:1], s[38:39], 0, v[66:67]
	v_lshl_add_u64 v[8:9], v[10:11], 0, s[60:61]
	s_waitcnt vmcnt(5)
	v_fmac_f32_e32 v81, v12, v80
	v_cndmask_b32_e64 v12, v12, v81, s[14:15]
	v_cndmask_b32_e64 v13, v230, v232, s[4:5]
	v_permlane32_swap_b32_e32 v14, v15
	v_lshl_add_u64 v[2:3], v[0:1], 0, v[10:11]
	v_lshl_add_u64 v[0:1], v[0:1], 0, v[8:9]
	v_cndmask_b32_e64 v14, v14, v15, s[6:7]
	v_mov_b32_e32 v15, v13
	v_mov_b32_e32 v80, v13
	s_waitcnt vmcnt(4)
	v_fmac_f32_e32 v83, v12, v82
	v_cndmask_b32_e64 v12, v12, v83, s[16:17]
	global_load_dwordx4 v[4:7], v[2:3], off nt
	s_nop 0
	global_load_dwordx4 v[0:3], v[0:1], off nt
	v_permlane32_swap_b32_e32 v15, v80
	v_cndmask_b32_e64 v81, v225, 1.0, s[4:5]
	v_cndmask_b32_e64 v15, v15, v80, s[6:7]
	v_cndmask_b32_e64 v82, v231, 0, s[4:5]
	v_mul_f32_e32 v83, v81, v14
	v_cndmask_b32_e64 v83, v83, v81, s[6:7]
	s_waitcnt vmcnt(5)
	v_fmac_f32_e32 v85, v12, v84
	v_cndmask_b32_e64 v12, v12, v85, s[18:19]
	v_fma_f32 v81, v81, v15, v82
	v_cndmask_b32_e64 v81, v81, v82, s[6:7]
	v_fma_f32 v80, v13, v14, v15
	v_fmac_f32_e32 v13, v229, v15
	v_mul_f32_e32 v14, v229, v14
	v_cndmask_b32_e64 v13, v13, v80, s[6:7]
	v_and_b32_e32 v15, 0xffff0000, v166
	v_lshlrev_b32_e32 v80, 16, v165
	v_mov_b32_e32 v84, v162
	s_waitcnt vmcnt(4)
	v_fmac_f32_e32 v87, v12, v86
	v_cndmask_b32_e64 v12, v12, v87, s[20:21]
	v_mul_f32_e32 v217, 0, v117
	v_mul_f32_e32 v216, 0, v124
	v_mul_f32_e32 v214, 0, v131
	v_mul_f32_e32 v213, 0, v142
	s_waitcnt vmcnt(3)
	v_fmac_f32_e32 v89, v12, v88
	v_cndmask_b32_e64 v12, v12, v89, s[22:23]
	s_add_i32 s75, s75, 1
	s_waitcnt vmcnt(2)
	v_fmac_f32_e32 v91, v12, v90
	v_cndmask_b32_e64 v12, v12, v91, s[24:25]
	v_fmac_f32_e32 v81, v83, v12
	v_fmac_f32_e32 v226, v157, v81
	v_cvt_pk_bf16_f32 v81, v226, v226
	ds_write_b16 v61, v81 offset:35840
	v_fmac_f32_e32 v211, v156, v226
	v_cvt_pk_bf16_f32 v81, v211, v211
	v_fmac_f32_e32 v13, v14, v12
	v_lshlrev_b32_e32 v14, 16, v166
	ds_write_b16 v61, v81 offset:36112
	v_fmac_f32_e32 v227, v155, v211
	v_cvt_pk_bf16_f32 v81, v227, v227
	v_add_f32_e32 v82, v224, v14
	ds_write_b16 v61, v81 offset:36384
	v_fmac_f32_e32 v228, v154, v227
	v_cvt_pk_bf16_f32 v81, v228, v228
	v_fma_f32 v82, v146, v82, v15
	ds_write_b16 v61, v81 offset:36656
	v_and_b32_e32 v81, 0xffff0000, v165
	v_fma_f32 v82, v145, v82, v80
	v_mov_b32_e32 v83, v162
	v_fma_f32 v82, v144, v82, v81
	s_nop 0
	v_permlane16_swap_b32_e32 v83, v84
	v_cndmask_b32_e64 v83, v83, v84, s[4:5]
	v_mov_b32_e32 v84, v82
	v_mov_b32_e32 v85, v82
	s_nop 1
	v_permlane16_swap_b32_e32 v84, v85
	v_cndmask_b32_e64 v84, v84, v85, s[4:5]
	v_mul_f32_e32 v85, v162, v83
	v_fma_f32 v86, v82, v83, v84
	v_fmac_f32_e32 v82, v162, v84
	v_cndmask_b32_e64 v82, v82, v86, s[4:5]
	v_mov_b32_e32 v86, v85
	v_mov_b32_e32 v87, v85
	s_nop 1
	v_permlane32_swap_b32_e32 v86, v87
	v_cndmask_b32_e64 v86, v86, v87, s[6:7]
	v_mov_b32_e32 v87, v82
	v_mov_b32_e32 v88, v82
	s_nop 1
	v_permlane32_swap_b32_e32 v87, v88
	v_cndmask_b32_e64 v83, v83, 1.0, s[4:5]
	v_cndmask_b32_e64 v87, v87, v88, s[6:7]
	v_cndmask_b32_e64 v84, v84, 0, s[4:5]
	v_mul_f32_e32 v89, v83, v86
	v_cndmask_b32_e64 v89, v89, v83, s[6:7]
	v_fma_f32 v83, v83, v87, v84
	v_cndmask_b32_e64 v83, v83, v84, s[6:7]
	v_fmac_f32_e32 v83, v13, v89
	v_fmac_f32_e32 v14, v147, v83
	v_cvt_pk_bf16_f32 v83, v14, v14
	ds_write_b16 v61, v83 offset:40192
	v_fmac_f32_e32 v15, v146, v14
	v_cvt_pk_bf16_f32 v14, v15, v15
	ds_write_b16 v61, v14 offset:40464
	v_fmac_f32_e32 v80, v145, v15
	v_cvt_pk_bf16_f32 v14, v80, v80
	v_fma_f32 v88, v82, v86, v87
	ds_write_b16 v61, v14 offset:40736
	v_fmac_f32_e32 v81, v144, v80
	v_cvt_pk_bf16_f32 v14, v81, v81
	v_fmac_f32_e32 v82, v85, v87
	ds_write_b16 v61, v14 offset:41008
	v_mul_f32_e32 v14, v85, v86
	v_cndmask_b32_e64 v15, v82, v88, s[6:7]
	v_fmac_f32_e32 v15, v13, v14
	v_lshlrev_b32_e32 v13, 16, v168
	v_and_b32_e32 v14, 0xffff0000, v168
	v_add_f32_e32 v82, v223, v13
	v_lshlrev_b32_e32 v80, 16, v167
	v_fma_f32 v82, v151, v82, v14
	v_and_b32_e32 v81, 0xffff0000, v167
	v_fma_f32 v82, v149, v82, v80
	v_mov_b32_e32 v83, v163
	v_mov_b32_e32 v84, v163
	v_fma_f32 v82, v148, v82, v81
	s_nop 0
	v_permlane16_swap_b32_e32 v83, v84
	v_cndmask_b32_e64 v83, v83, v84, s[4:5]
	v_mov_b32_e32 v84, v82
	v_mov_b32_e32 v85, v82
	s_nop 1
	v_permlane16_swap_b32_e32 v84, v85
	v_cndmask_b32_e64 v84, v84, v85, s[4:5]
	v_mul_f32_e32 v85, v163, v83
	v_fma_f32 v86, v82, v83, v84
	v_fmac_f32_e32 v82, v163, v84
	v_cndmask_b32_e64 v82, v82, v86, s[4:5]
	v_mov_b32_e32 v86, v85
	v_mov_b32_e32 v87, v85
	s_nop 1
	v_permlane32_swap_b32_e32 v86, v87
	v_cndmask_b32_e64 v86, v86, v87, s[6:7]
	v_mov_b32_e32 v87, v82
	v_mov_b32_e32 v88, v82
	s_nop 1
	v_permlane32_swap_b32_e32 v87, v88
	v_cndmask_b32_e64 v83, v83, 1.0, s[4:5]
	v_cndmask_b32_e64 v87, v87, v88, s[6:7]
	v_cndmask_b32_e64 v84, v84, 0, s[4:5]
	v_mul_f32_e32 v89, v83, v86
	v_cndmask_b32_e64 v89, v89, v83, s[6:7]
	v_fma_f32 v83, v83, v87, v84
	v_cndmask_b32_e64 v83, v83, v84, s[6:7]
	v_fmac_f32_e32 v83, v15, v89
	v_fmac_f32_e32 v13, v153, v83
	v_cvt_pk_bf16_f32 v83, v13, v13
	ds_write_b16 v61, v83 offset:44544
	v_fmac_f32_e32 v14, v151, v13
	v_cvt_pk_bf16_f32 v13, v14, v14
	ds_write_b16 v61, v13 offset:44816
	v_fmac_f32_e32 v80, v149, v14
	v_cvt_pk_bf16_f32 v13, v80, v80
	v_fma_f32 v88, v82, v86, v87
	ds_write_b16 v61, v13 offset:45088
	v_fmac_f32_e32 v81, v148, v80
	v_cvt_pk_bf16_f32 v13, v81, v81
	v_fmac_f32_e32 v82, v85, v87
	ds_write_b16 v61, v13 offset:45360
	v_mul_f32_e32 v13, v85, v86
	v_cndmask_b32_e64 v84, v82, v88, s[6:7]
	v_fmac_f32_e32 v84, v15, v13
	v_lshlrev_b32_e32 v13, 16, v170
	v_and_b32_e32 v14, 0xffff0000, v170
	v_add_f32_e32 v81, v222, v13
	v_lshlrev_b32_e32 v15, 16, v169
	v_fma_f32 v81, v160, v81, v14
	v_and_b32_e32 v80, 0xffff0000, v169
	v_fma_f32 v81, v159, v81, v15
	v_mov_b32_e32 v82, v164
	v_mov_b32_e32 v83, v164
	v_fma_f32 v81, v158, v81, v80
	s_nop 0
	v_permlane16_swap_b32_e32 v82, v83
	v_cndmask_b32_e64 v82, v82, v83, s[4:5]
	v_mov_b32_e32 v83, v81
	v_mov_b32_e32 v85, v81
	s_nop 1
	v_permlane16_swap_b32_e32 v83, v85
	v_cndmask_b32_e64 v83, v83, v85, s[4:5]
	v_mul_f32_e32 v85, v164, v82
	v_fma_f32 v86, v81, v82, v83
	v_fmac_f32_e32 v81, v164, v83
	v_cndmask_b32_e64 v86, v81, v86, s[4:5]
	v_mov_b32_e32 v81, v85
	v_mov_b32_e32 v87, v85
	s_nop 1
	v_permlane32_swap_b32_e32 v81, v87
	v_cndmask_b32_e64 v87, v81, v87, s[6:7]
	v_mov_b32_e32 v81, v86
	v_mov_b32_e32 v88, v86
	s_nop 1
	v_permlane32_swap_b32_e32 v81, v88
	v_cndmask_b32_e64 v88, v81, v88, s[6:7]
	v_cndmask_b32_e64 v81, v82, 1.0, s[4:5]
	v_cndmask_b32_e64 v82, v83, 0, s[4:5]
	v_mul_f32_e32 v83, v81, v87
	v_cndmask_b32_e64 v83, v83, v81, s[6:7]
	v_fma_f32 v81, v81, v88, v82
	v_cndmask_b32_e64 v81, v81, v82, s[6:7]
	v_fmac_f32_e32 v81, v84, v83
	v_fmac_f32_e32 v13, v161, v81
	v_cvt_pk_bf16_f32 v81, v13, v13
	ds_write_b16 v61, v81 offset:48896
	v_fmac_f32_e32 v14, v160, v13
	v_cvt_pk_bf16_f32 v13, v14, v14
	ds_write_b16 v61, v13 offset:49168
	v_fmac_f32_e32 v15, v159, v14
	v_cvt_pk_bf16_f32 v13, v15, v15
	ds_write_b16 v61, v13 offset:49440
	v_fmac_f32_e32 v80, v158, v15
	v_cvt_pk_bf16_f32 v13, v80, v80
	ds_write_b16 v61, v13 offset:49712
	v_lshlrev_b32_e32 v13, 1, v210
	v_mul_lo_u32 v14, v209, s67
	v_add3_u32 v13, 0, v13, v14
	s_waitcnt lgkmcnt(0)
	s_barrier
	ds_read_b128 v[80:83], v13 offset:35840
	s_waitcnt vmcnt(1)
	v_lshlrev_b32_e32 v14, 16, v4
	v_and_b32_e32 v4, 0xffff0000, v4
	v_fma_f32 v89, v86, v87, v88
	v_fmac_f32_e32 v86, v85, v88
	s_waitcnt lgkmcnt(0)
	v_lshlrev_b32_e32 v15, 16, v80
	v_mul_f32_e32 v14, v15, v14
	v_and_b32_e32 v15, 0xffff0000, v80
	v_mul_f32_e32 v4, v15, v4
	v_cvt_pk_bf16_f32 v4, v14, v4
	v_lshlrev_b32_e32 v14, 16, v5
	v_lshlrev_b32_e32 v15, 16, v81
	v_mul_f32_e32 v14, v15, v14
	v_and_b32_e32 v15, 0xffff0000, v81
	v_and_b32_e32 v5, 0xffff0000, v5
	v_mul_f32_e32 v5, v15, v5
	v_cvt_pk_bf16_f32 v5, v14, v5
	v_lshlrev_b32_e32 v14, 16, v6
	v_lshlrev_b32_e32 v15, 16, v82
	v_mul_f32_e32 v14, v15, v14
	v_and_b32_e32 v15, 0xffff0000, v82
	v_and_b32_e32 v6, 0xffff0000, v6
	v_mul_f32_e32 v6, v15, v6
	v_cvt_pk_bf16_f32 v6, v14, v6
	v_lshlrev_b32_e32 v14, 16, v7
	v_lshlrev_b32_e32 v15, 16, v83
	v_mul_f32_e32 v14, v15, v14
	v_and_b32_e32 v15, 0xffff0000, v83
	v_and_b32_e32 v7, 0xffff0000, v7
	v_mul_f32_e32 v7, v15, v7
	v_cvt_pk_bf16_f32 v7, v14, v7
	ds_read_b128 v[80:83], v13 offset:44544
	v_lshl_add_u64 v[14:15], s[52:53], 0, v[66:67]
	v_lshl_add_u64 v[10:11], v[14:15], 0, v[10:11]
	global_store_dwordx4 v[10:11], v[4:7], off sc1
	v_mul_f32_e32 v87, v85, v87
	v_mov_b32_e32 v85, v188
	s_waitcnt vmcnt(1)
	v_lshlrev_b32_e32 v4, 16, v0
	s_waitcnt lgkmcnt(0)
	v_lshlrev_b32_e32 v5, 16, v80
	v_mul_f32_e32 v4, v5, v4
	v_and_b32_e32 v5, 0xffff0000, v80
	v_and_b32_e32 v0, 0xffff0000, v0
	v_mul_f32_e32 v0, v5, v0
	v_cvt_pk_bf16_f32 v0, v4, v0
	v_lshlrev_b32_e32 v4, 16, v1
	v_lshlrev_b32_e32 v5, 16, v81
	v_mul_f32_e32 v4, v5, v4
	v_and_b32_e32 v5, 0xffff0000, v81
	v_and_b32_e32 v1, 0xffff0000, v1
	v_mul_f32_e32 v1, v5, v1
	v_cvt_pk_bf16_f32 v1, v4, v1
	v_lshlrev_b32_e32 v4, 16, v2
	v_lshlrev_b32_e32 v5, 16, v82
	v_mul_f32_e32 v4, v5, v4
	v_and_b32_e32 v5, 0xffff0000, v82
	v_and_b32_e32 v2, 0xffff0000, v2
	v_mul_f32_e32 v2, v5, v2
	v_cvt_pk_bf16_f32 v2, v4, v2
	v_lshlrev_b32_e32 v4, 16, v3
	v_lshlrev_b32_e32 v5, 16, v83
	v_mul_f32_e32 v4, v5, v4
	v_and_b32_e32 v5, 0xffff0000, v83
	v_and_b32_e32 v3, 0xffff0000, v3
	v_mul_f32_e32 v3, v5, v3
	v_cvt_pk_bf16_f32 v3, v4, v3
	v_lshl_add_u64 v[4:5], v[14:15], 0, v[8:9]
	v_cndmask_b32_e64 v15, v86, v89, s[6:7]
	v_lshlrev_b32_e32 v80, 16, v193
	v_fmac_f32_e32 v15, v84, v87
	v_and_b32_e32 v81, 0xffff0000, v193
	v_add_f32_e32 v84, v221, v80
	v_lshlrev_b32_e32 v82, 16, v192
	v_fma_f32 v84, v173, v84, v81
	v_and_b32_e32 v83, 0xffff0000, v192
	v_fma_f32 v84, v172, v84, v82
	v_mov_b32_e32 v86, v188
	v_fma_f32 v84, v171, v84, v83
	s_nop 0
	v_permlane16_swap_b32_e32 v85, v86
	v_cndmask_b32_e64 v85, v85, v86, s[4:5]
	v_mov_b32_e32 v86, v84
	v_mov_b32_e32 v87, v84
	global_store_dwordx4 v[4:5], v[0:3], off sc1
	s_nop 0
	v_permlane16_swap_b32_e32 v86, v87
	v_mov_b32_e32 v0, v60
	s_barrier
	v_cndmask_b32_e64 v86, v86, v87, s[4:5]
	v_lshlrev_b32_e32 v1, 3, v0
	v_and_b32_e32 v13, 0x78, v1
	v_ashrrev_i32_e32 v14, 4, v0
	v_mul_f32_e32 v87, v188, v85
	v_fma_f32 v88, v84, v85, v86
	v_fmac_f32_e32 v84, v188, v86
	v_or_b32_e32 v1, s37, v13
	v_add3_u32 v0, v14, s77, 64
	v_cndmask_b32_e64 v84, v84, v88, s[4:5]
	v_mov_b32_e32 v88, v87
	v_mov_b32_e32 v89, v87
	v_lshlrev_b32_e32 v66, 1, v1
	v_ashrrev_i32_e32 v1, 31, v0
	v_permlane32_swap_b32_e32 v88, v89
	v_lshl_add_u64 v[2:3], s[38:39], 0, v[66:67]
	v_lshlrev_b64 v[10:11], 11, v[0:1]
	v_cndmask_b32_e64 v88, v88, v89, s[6:7]
	v_mov_b32_e32 v89, v84
	v_mov_b32_e32 v90, v84
	v_lshl_add_u64 v[0:1], v[2:3], 0, v[10:11]
	s_nop 0
	v_permlane32_swap_b32_e32 v89, v90
	v_cndmask_b32_e64 v85, v85, 1.0, s[4:5]
	global_load_dwordx4 v[4:7], v[0:1], off nt
	v_cndmask_b32_e64 v89, v89, v90, s[6:7]
	v_cndmask_b32_e64 v86, v86, 0, s[4:5]
	v_mul_f32_e32 v91, v85, v88
	v_cndmask_b32_e64 v91, v91, v85, s[6:7]
	v_fma_f32 v85, v85, v89, v86
	v_cndmask_b32_e64 v85, v85, v86, s[6:7]
	v_lshl_add_u64 v[8:9], v[10:11], 0, s[60:61]
	v_fmac_f32_e32 v85, v15, v91
	v_lshl_add_u64 v[0:1], v[2:3], 0, v[8:9]
	v_fmac_f32_e32 v80, v174, v85
	global_load_dwordx4 v[0:3], v[0:1], off nt
	v_cvt_pk_bf16_f32 v85, v80, v80
	ds_write_b16 v61, v85 offset:35840
	v_fmac_f32_e32 v81, v173, v80
	v_cvt_pk_bf16_f32 v80, v81, v81
	ds_write_b16 v61, v80 offset:36112
	v_fmac_f32_e32 v82, v172, v81
	v_cvt_pk_bf16_f32 v80, v82, v82
	v_fma_f32 v90, v84, v88, v89
	ds_write_b16 v61, v80 offset:36384
	v_fmac_f32_e32 v83, v171, v82
	v_cvt_pk_bf16_f32 v80, v83, v83
	v_fmac_f32_e32 v84, v87, v89
	ds_write_b16 v61, v80 offset:36656
	v_mul_f32_e32 v80, v87, v88
	v_cndmask_b32_e64 v81, v84, v90, s[6:7]
	v_fmac_f32_e32 v81, v15, v80
	v_lshlrev_b32_e32 v15, 16, v195
	v_and_b32_e32 v80, 0xffff0000, v195
	v_add_f32_e32 v84, v220, v15
	v_lshlrev_b32_e32 v82, 16, v194
	v_fma_f32 v84, v177, v84, v80
	v_and_b32_e32 v83, 0xffff0000, v194
	v_fma_f32 v84, v176, v84, v82
	v_mov_b32_e32 v85, v189
	v_mov_b32_e32 v86, v189
	v_fma_f32 v84, v175, v84, v83
	s_nop 0
	v_permlane16_swap_b32_e32 v85, v86
	v_cndmask_b32_e64 v85, v85, v86, s[4:5]
	v_mov_b32_e32 v86, v84
	v_mov_b32_e32 v87, v84
	s_nop 1
	v_permlane16_swap_b32_e32 v86, v87
	v_cndmask_b32_e64 v86, v86, v87, s[4:5]
	v_mul_f32_e32 v87, v189, v85
	v_fma_f32 v88, v84, v85, v86
	v_fmac_f32_e32 v84, v189, v86
	v_cndmask_b32_e64 v84, v84, v88, s[4:5]
	v_mov_b32_e32 v88, v87
	v_mov_b32_e32 v89, v87
	s_nop 1
	v_permlane32_swap_b32_e32 v88, v89
	v_cndmask_b32_e64 v88, v88, v89, s[6:7]
	v_mov_b32_e32 v89, v84
	v_mov_b32_e32 v90, v84
	s_nop 1
	v_permlane32_swap_b32_e32 v89, v90
	v_cndmask_b32_e64 v85, v85, 1.0, s[4:5]
	v_cndmask_b32_e64 v89, v89, v90, s[6:7]
	v_cndmask_b32_e64 v86, v86, 0, s[4:5]
	v_mul_f32_e32 v91, v85, v88
	v_cndmask_b32_e64 v91, v91, v85, s[6:7]
	v_fma_f32 v85, v85, v89, v86
	v_cndmask_b32_e64 v85, v85, v86, s[6:7]
	v_fmac_f32_e32 v85, v81, v91
	v_fmac_f32_e32 v15, v178, v85
	v_cvt_pk_bf16_f32 v85, v15, v15
	ds_write_b16 v61, v85 offset:40192
	v_fmac_f32_e32 v80, v177, v15
	v_cvt_pk_bf16_f32 v15, v80, v80
	ds_write_b16 v61, v15 offset:40464
	v_fmac_f32_e32 v82, v176, v80
	v_cvt_pk_bf16_f32 v15, v82, v82
	v_fma_f32 v90, v84, v88, v89
	ds_write_b16 v61, v15 offset:40736
	v_fmac_f32_e32 v83, v175, v82
	v_cvt_pk_bf16_f32 v15, v83, v83
	v_fmac_f32_e32 v84, v87, v89
	ds_write_b16 v61, v15 offset:41008
	v_mul_f32_e32 v15, v87, v88
	v_cndmask_b32_e64 v80, v84, v90, s[6:7]
	v_fmac_f32_e32 v80, v81, v15
	v_lshlrev_b32_e32 v15, 16, v197
	v_and_b32_e32 v81, 0xffff0000, v197
	v_add_f32_e32 v84, v219, v15
	v_lshlrev_b32_e32 v82, 16, v196
	v_fma_f32 v84, v181, v84, v81
	v_and_b32_e32 v83, 0xffff0000, v196
	v_fma_f32 v84, v180, v84, v82
	v_mov_b32_e32 v85, v190
	v_mov_b32_e32 v86, v190
	v_fma_f32 v84, v179, v84, v83
	s_nop 0
	v_permlane16_swap_b32_e32 v85, v86
	v_cndmask_b32_e64 v85, v85, v86, s[4:5]
	v_mov_b32_e32 v86, v84
	v_mov_b32_e32 v87, v84
	s_nop 1
	v_permlane16_swap_b32_e32 v86, v87
	v_cndmask_b32_e64 v86, v86, v87, s[4:5]
	v_mul_f32_e32 v87, v190, v85
	v_fma_f32 v88, v84, v85, v86
	v_fmac_f32_e32 v84, v190, v86
	v_cndmask_b32_e64 v84, v84, v88, s[4:5]
	v_mov_b32_e32 v88, v87
	v_mov_b32_e32 v89, v87
	s_nop 1
	v_permlane32_swap_b32_e32 v88, v89
	v_cndmask_b32_e64 v88, v88, v89, s[6:7]
	v_mov_b32_e32 v89, v84
	v_mov_b32_e32 v90, v84
	s_nop 1
	v_permlane32_swap_b32_e32 v89, v90
	v_cndmask_b32_e64 v85, v85, 1.0, s[4:5]
	v_cndmask_b32_e64 v89, v89, v90, s[6:7]
	v_cndmask_b32_e64 v86, v86, 0, s[4:5]
	v_mul_f32_e32 v91, v85, v88
	v_cndmask_b32_e64 v91, v91, v85, s[6:7]
	v_fma_f32 v85, v85, v89, v86
	v_cndmask_b32_e64 v85, v85, v86, s[6:7]
	v_fmac_f32_e32 v85, v80, v91
	v_fmac_f32_e32 v15, v182, v85
	v_cvt_pk_bf16_f32 v85, v15, v15
	ds_write_b16 v61, v85 offset:44544
	v_fmac_f32_e32 v81, v181, v15
	v_cvt_pk_bf16_f32 v15, v81, v81
	ds_write_b16 v61, v15 offset:44816
	v_fmac_f32_e32 v82, v180, v81
	v_cvt_pk_bf16_f32 v15, v82, v82
	v_fma_f32 v90, v84, v88, v89
	ds_write_b16 v61, v15 offset:45088
	v_fmac_f32_e32 v83, v179, v82
	v_cvt_pk_bf16_f32 v15, v83, v83
	v_fmac_f32_e32 v84, v87, v89
	ds_write_b16 v61, v15 offset:45360
	v_mul_f32_e32 v15, v87, v88
	v_cndmask_b32_e64 v84, v84, v90, s[6:7]
	v_fmac_f32_e32 v84, v80, v15
	v_lshlrev_b32_e32 v15, 16, v199
	v_and_b32_e32 v80, 0xffff0000, v199
	v_add_f32_e32 v83, v218, v15
	v_lshlrev_b32_e32 v81, 16, v198
	v_fma_f32 v83, v186, v83, v80
	v_and_b32_e32 v82, 0xffff0000, v198
	v_fma_f32 v83, v185, v83, v81
	v_mov_b32_e32 v85, v191
	v_mov_b32_e32 v86, v191
	v_fma_f32 v83, v184, v83, v82
	s_nop 0
	v_permlane16_swap_b32_e32 v85, v86
	v_cndmask_b32_e64 v85, v85, v86, s[4:5]
	v_mov_b32_e32 v86, v83
	v_mov_b32_e32 v87, v83
	s_nop 1
	v_permlane16_swap_b32_e32 v86, v87
	v_cndmask_b32_e64 v86, v86, v87, s[4:5]
	v_mul_f32_e32 v87, v191, v85
	v_fma_f32 v88, v83, v85, v86
	v_fmac_f32_e32 v83, v191, v86
	v_cndmask_b32_e64 v88, v83, v88, s[4:5]
	v_mov_b32_e32 v83, v87
	v_mov_b32_e32 v89, v87
	s_nop 1
	v_permlane32_swap_b32_e32 v83, v89
	v_cndmask_b32_e64 v89, v83, v89, s[6:7]
	v_mov_b32_e32 v83, v88
	v_mov_b32_e32 v90, v88
	s_nop 1
	v_permlane32_swap_b32_e32 v83, v90
	v_cndmask_b32_e64 v90, v83, v90, s[6:7]
	v_cndmask_b32_e64 v83, v85, 1.0, s[4:5]
	v_cndmask_b32_e64 v85, v86, 0, s[4:5]
	v_mul_f32_e32 v86, v83, v89
	v_cndmask_b32_e64 v86, v86, v83, s[6:7]
	v_fma_f32 v83, v83, v90, v85
	v_cndmask_b32_e64 v83, v83, v85, s[6:7]
	v_fmac_f32_e32 v83, v84, v86
	v_fmac_f32_e32 v15, v187, v83
	v_fmac_f32_e32 v80, v186, v15
	v_cvt_pk_bf16_f32 v83, v15, v15
	ds_write_b16 v61, v83 offset:48896
	v_cvt_pk_bf16_f32 v15, v80, v80
	v_fmac_f32_e32 v81, v185, v80
	v_lshlrev_b32_e32 v13, 1, v13
	v_mul_lo_u32 v14, v14, s67
	ds_write_b16 v61, v15 offset:49168
	v_cvt_pk_bf16_f32 v15, v81, v81
	v_fmac_f32_e32 v82, v184, v81
	v_add3_u32 v13, 0, v13, v14
	ds_write_b16 v61, v15 offset:49440
	v_cvt_pk_bf16_f32 v15, v82, v82
	ds_write_b16 v61, v15 offset:49712
	s_waitcnt lgkmcnt(0)
	s_barrier
	ds_read_b128 v[80:83], v13 offset:35840
	s_waitcnt vmcnt(1)
	v_lshlrev_b32_e32 v14, 16, v4
	v_and_b32_e32 v4, 0xffff0000, v4
	v_fma_f32 v85, v88, v89, v90
	v_fmac_f32_e32 v88, v87, v90
	s_waitcnt lgkmcnt(0)
	v_lshlrev_b32_e32 v15, 16, v80
	v_mul_f32_e32 v14, v15, v14
	v_and_b32_e32 v15, 0xffff0000, v80
	v_mul_f32_e32 v4, v15, v4
	v_cvt_pk_bf16_f32 v4, v14, v4
	v_lshlrev_b32_e32 v14, 16, v5
	v_lshlrev_b32_e32 v15, 16, v81
	v_mul_f32_e32 v14, v15, v14
	v_and_b32_e32 v15, 0xffff0000, v81
	v_and_b32_e32 v5, 0xffff0000, v5
	v_mul_f32_e32 v5, v15, v5
	v_cvt_pk_bf16_f32 v5, v14, v5
	v_lshlrev_b32_e32 v14, 16, v6
	v_lshlrev_b32_e32 v15, 16, v82
	v_mul_f32_e32 v14, v15, v14
	v_and_b32_e32 v15, 0xffff0000, v82
	v_and_b32_e32 v6, 0xffff0000, v6
	v_mul_f32_e32 v6, v15, v6
	v_cvt_pk_bf16_f32 v6, v14, v6
	v_lshlrev_b32_e32 v14, 16, v7
	v_lshlrev_b32_e32 v15, 16, v83
	v_mul_f32_e32 v14, v15, v14
	v_and_b32_e32 v15, 0xffff0000, v83
	v_and_b32_e32 v7, 0xffff0000, v7
	v_mul_f32_e32 v7, v15, v7
	v_cvt_pk_bf16_f32 v7, v14, v7
	ds_read_b128 v[80:83], v13 offset:44544
	v_lshl_add_u64 v[14:15], s[52:53], 0, v[66:67]
	v_lshl_add_u64 v[10:11], v[14:15], 0, v[10:11]
	global_store_dwordx4 v[10:11], v[4:7], off sc1
	v_mul_f32_e32 v86, v87, v89
	s_add_i32 s24, s76, 1
	s_waitcnt vmcnt(1)
	v_lshlrev_b32_e32 v4, 16, v0
	s_waitcnt lgkmcnt(0)
	v_lshlrev_b32_e32 v5, 16, v80
	v_mul_f32_e32 v4, v5, v4
	v_and_b32_e32 v5, 0xffff0000, v80
	v_and_b32_e32 v0, 0xffff0000, v0
	v_mul_f32_e32 v0, v5, v0
	v_cvt_pk_bf16_f32 v0, v4, v0
	v_lshlrev_b32_e32 v4, 16, v1
	v_lshlrev_b32_e32 v5, 16, v81
	v_mul_f32_e32 v4, v5, v4
	v_and_b32_e32 v5, 0xffff0000, v81
	v_and_b32_e32 v1, 0xffff0000, v1
	v_mul_f32_e32 v1, v5, v1
	v_cvt_pk_bf16_f32 v1, v4, v1
	v_lshlrev_b32_e32 v4, 16, v2
	v_lshlrev_b32_e32 v5, 16, v82
	v_mul_f32_e32 v4, v5, v4
	v_and_b32_e32 v5, 0xffff0000, v82
	v_and_b32_e32 v2, 0xffff0000, v2
	v_mul_f32_e32 v2, v5, v2
	v_cvt_pk_bf16_f32 v2, v4, v2
	v_lshlrev_b32_e32 v4, 16, v3
	v_lshlrev_b32_e32 v5, 16, v83
	v_mul_f32_e32 v4, v5, v4
	v_and_b32_e32 v5, 0xffff0000, v83
	v_and_b32_e32 v3, 0xffff0000, v3
	v_mul_f32_e32 v3, v5, v3
	v_cvt_pk_bf16_f32 v3, v4, v3
	v_lshl_add_u64 v[4:5], v[14:15], 0, v[8:9]
	v_cndmask_b32_e64 v80, v88, v85, s[6:7]
	v_lshlrev_b32_e32 v15, 16, v208
	v_fmac_f32_e32 v80, v84, v86
	v_and_b32_e32 v81, 0xffff0000, v208
	v_add_f32_e32 v84, v215, v15
	v_lshlrev_b32_e32 v82, 16, v207
	v_fma_f32 v84, v202, v84, v81
	v_and_b32_e32 v83, 0xffff0000, v207
	v_fma_f32 v84, v201, v84, v82
	v_mov_b32_e32 v85, v204
	v_mov_b32_e32 v86, v204
	v_fma_f32 v84, v200, v84, v83
	s_nop 0
	v_permlane16_swap_b32_e32 v85, v86
	global_store_dwordx4 v[4:5], v[0:3], off sc1
	v_cndmask_b32_e64 v85, v85, v86, s[4:5]
	v_mov_b32_e32 v86, v84
	v_mov_b32_e32 v0, v60
	v_mov_b32_e32 v87, v84
	s_barrier
	s_nop 0
	v_permlane16_swap_b32_e32 v86, v87
	v_lshlrev_b32_e32 v1, 3, v0
	v_ashrrev_i32_e32 v13, 4, v0
	v_and_b32_e32 v14, 0x78, v1
	v_add_u32_e32 v0, s77, v13
	v_cndmask_b32_e64 v86, v86, v87, s[4:5]
	v_or_b32_e32 v1, s37, v14
	v_add_u32_e32 v0, 0x80, v0
	v_mul_f32_e32 v87, v204, v85
	v_fma_f32 v88, v84, v85, v86
	v_fmac_f32_e32 v84, v204, v86
	v_lshlrev_b32_e32 v66, 1, v1
	v_ashrrev_i32_e32 v1, 31, v0
	v_cndmask_b32_e64 v84, v84, v88, s[4:5]
	v_mov_b32_e32 v88, v87
	v_mov_b32_e32 v89, v87
	v_lshl_add_u64 v[2:3], s[38:39], 0, v[66:67]
	v_lshlrev_b64 v[10:11], 11, v[0:1]
	v_permlane32_swap_b32_e32 v88, v89
	v_lshl_add_u64 v[0:1], v[2:3], 0, v[10:11]
	v_cndmask_b32_e64 v88, v88, v89, s[6:7]
	v_mov_b32_e32 v89, v84
	v_mov_b32_e32 v90, v84
	global_load_dwordx4 v[4:7], v[0:1], off nt
	s_nop 0
	v_permlane32_swap_b32_e32 v89, v90
	v_cndmask_b32_e64 v85, v85, 1.0, s[4:5]
	v_cndmask_b32_e64 v89, v89, v90, s[6:7]
	v_cndmask_b32_e64 v86, v86, 0, s[4:5]
	v_mul_f32_e32 v91, v85, v88
	v_cndmask_b32_e64 v91, v91, v85, s[6:7]
	v_fma_f32 v85, v85, v89, v86
	v_cndmask_b32_e64 v85, v85, v86, s[6:7]
	v_lshl_add_u64 v[8:9], v[10:11], 0, s[60:61]
	v_fmac_f32_e32 v85, v80, v91
	v_lshl_add_u64 v[0:1], v[2:3], 0, v[8:9]
	v_fmac_f32_e32 v15, v203, v85
	global_load_dwordx4 v[0:3], v[0:1], off nt
	v_cvt_pk_bf16_f32 v85, v15, v15
	ds_write_b16 v61, v85 offset:35840
	v_fmac_f32_e32 v81, v202, v15
	v_cvt_pk_bf16_f32 v15, v81, v81
	ds_write_b16 v61, v15 offset:36112
	v_fmac_f32_e32 v82, v201, v81
	v_cvt_pk_bf16_f32 v15, v82, v82
	v_fma_f32 v90, v84, v88, v89
	ds_write_b16 v61, v15 offset:36384
	v_fmac_f32_e32 v83, v200, v82
	v_cvt_pk_bf16_f32 v15, v83, v83
	v_fmac_f32_e32 v84, v87, v89
	ds_write_b16 v61, v15 offset:36656
	v_mul_f32_e32 v81, v87, v88
	v_cndmask_b32_e64 v15, v84, v90, s[6:7]
	v_lshlrev_b32_e32 v82, 16, v206
	v_fmac_f32_e32 v15, v80, v81
	v_and_b32_e32 v85, 0xffff0000, v206
	v_add_f32_e32 v80, v212, v82
	v_lshlrev_b32_e32 v86, 16, v205
	v_fma_f32 v80, v134, v80, v85
	v_and_b32_e32 v87, 0xffff0000, v205
	v_fma_f32 v80, v133, v80, v86
	v_mov_b32_e32 v81, v183
	v_mov_b32_e32 v83, v183
	v_fma_f32 v80, v132, v80, v87
	s_nop 0
	v_permlane16_swap_b32_e32 v81, v83
	v_cndmask_b32_e64 v88, v81, v83, s[4:5]
	v_mov_b32_e32 v81, v80
	v_mov_b32_e32 v83, v80
	s_nop 1
	v_permlane16_swap_b32_e32 v81, v83
	v_cndmask_b32_e64 v89, v81, v83, s[4:5]
	v_mul_f32_e32 v83, v183, v88
	v_fma_f32 v81, v80, v88, v89
	v_fmac_f32_e32 v80, v183, v89
	v_cndmask_b32_e64 v80, v80, v81, s[4:5]
	v_mov_b32_e32 v81, v83
	v_mov_b32_e32 v84, v83
	s_nop 1
	v_permlane32_swap_b32_e32 v81, v84
	v_cndmask_b32_e64 v90, v81, v84, s[6:7]
	v_mov_b32_e32 v81, v80
	v_mov_b32_e32 v84, v80
	s_nop 1
	v_permlane32_swap_b32_e32 v81, v84
	v_cndmask_b32_e64 v88, v88, 1.0, s[4:5]
	v_cndmask_b32_e64 v84, v81, v84, s[6:7]
	v_cndmask_b32_e64 v89, v89, 0, s[4:5]
	v_mul_f32_e32 v91, v88, v90
	v_cndmask_b32_e64 v91, v91, v88, s[6:7]
	v_fma_f32 v88, v88, v84, v89
	v_cndmask_b32_e64 v88, v88, v89, s[6:7]
	v_fmac_f32_e32 v88, v15, v91
	v_fmac_f32_e32 v82, v135, v88
	v_cvt_pk_bf16_f32 v88, v82, v82
	ds_write_b16 v61, v88 offset:40192
	v_fmac_f32_e32 v85, v134, v82
	v_cvt_pk_bf16_f32 v82, v85, v85
	ds_write_b16 v61, v82 offset:40464
	v_fmac_f32_e32 v86, v133, v85
	v_cvt_pk_bf16_f32 v82, v86, v86
	v_fma_f32 v81, v80, v90, v84
	ds_write_b16 v61, v82 offset:40736
	v_fmac_f32_e32 v87, v132, v86
	v_cvt_pk_bf16_f32 v82, v87, v87
	v_fmac_f32_e32 v80, v83, v84
	ds_write_b16 v61, v82 offset:41008
	v_mul_f32_e32 v82, v83, v90
	v_cndmask_b32_e64 v80, v80, v81, s[6:7]
	v_fmac_f32_e32 v80, v15, v82
	v_lshlrev_b32_e32 v15, 16, v103
	v_and_b32_e32 v81, 0xffff0000, v103
	v_add_f32_e32 v84, v112, v15
	v_lshlrev_b32_e32 v82, 16, v102
	v_fma_f32 v84, v99, v84, v81
	v_and_b32_e32 v83, 0xffff0000, v102
	v_fma_f32 v84, v98, v84, v82
	v_mov_b32_e32 v85, v101
	v_mov_b32_e32 v86, v101
	v_fma_f32 v84, v97, v84, v83
	s_nop 0
	v_permlane16_swap_b32_e32 v85, v86
	v_cndmask_b32_e64 v85, v85, v86, s[4:5]
	v_mov_b32_e32 v86, v84
	v_mov_b32_e32 v87, v84
	s_nop 1
	v_permlane16_swap_b32_e32 v86, v87
	v_cndmask_b32_e64 v86, v86, v87, s[4:5]
	v_mul_f32_e32 v87, v101, v85
	v_fma_f32 v88, v84, v85, v86
	v_fmac_f32_e32 v84, v101, v86
	v_cndmask_b32_e64 v84, v84, v88, s[4:5]
	v_mov_b32_e32 v88, v87
	v_mov_b32_e32 v89, v87
	s_nop 1
	v_permlane32_swap_b32_e32 v88, v89
	v_cndmask_b32_e64 v88, v88, v89, s[6:7]
	v_mov_b32_e32 v89, v84
	v_mov_b32_e32 v90, v84
	s_nop 1
	v_permlane32_swap_b32_e32 v89, v90
	v_cndmask_b32_e64 v85, v85, 1.0, s[4:5]
	v_cndmask_b32_e64 v89, v89, v90, s[6:7]
	v_cndmask_b32_e64 v86, v86, 0, s[4:5]
	v_mul_f32_e32 v91, v85, v88
	v_cndmask_b32_e64 v91, v91, v85, s[6:7]
	v_fma_f32 v85, v85, v89, v86
	v_cndmask_b32_e64 v85, v85, v86, s[6:7]
	v_fmac_f32_e32 v85, v80, v91
	v_fmac_f32_e32 v15, v100, v85
	v_cvt_pk_bf16_f32 v85, v15, v15
	ds_write_b16 v61, v85 offset:44544
	v_fmac_f32_e32 v81, v99, v15
	v_cvt_pk_bf16_f32 v15, v81, v81
	ds_write_b16 v61, v15 offset:44816
	v_fmac_f32_e32 v82, v98, v81
	v_cvt_pk_bf16_f32 v15, v82, v82
	v_fma_f32 v90, v84, v88, v89
	ds_write_b16 v61, v15 offset:45088
	v_fmac_f32_e32 v83, v97, v82
	v_cvt_pk_bf16_f32 v15, v83, v83
	v_fmac_f32_e32 v84, v87, v89
	ds_write_b16 v61, v15 offset:45360
	v_mul_f32_e32 v15, v87, v88
	v_cndmask_b32_e64 v84, v84, v90, s[6:7]
	v_fmac_f32_e32 v84, v80, v15
	v_lshlrev_b32_e32 v15, 16, v110
	v_and_b32_e32 v80, 0xffff0000, v110
	v_add_f32_e32 v83, v111, v15
	v_lshlrev_b32_e32 v81, 16, v109
	v_fma_f32 v83, v106, v83, v80
	v_and_b32_e32 v82, 0xffff0000, v109
	v_fma_f32 v83, v105, v83, v81
	v_mov_b32_e32 v85, v108
	v_mov_b32_e32 v86, v108
	v_fma_f32 v83, v104, v83, v82
	s_nop 0
	v_permlane16_swap_b32_e32 v85, v86
	v_cndmask_b32_e64 v85, v85, v86, s[4:5]
	v_mov_b32_e32 v86, v83
	v_mov_b32_e32 v87, v83
	s_nop 1
	v_permlane16_swap_b32_e32 v86, v87
	v_cndmask_b32_e64 v86, v86, v87, s[4:5]
	v_mul_f32_e32 v87, v108, v85
	v_fma_f32 v88, v83, v85, v86
	v_fmac_f32_e32 v83, v108, v86
	v_cndmask_b32_e64 v88, v83, v88, s[4:5]
	v_mov_b32_e32 v83, v87
	v_mov_b32_e32 v89, v87
	s_nop 1
	v_permlane32_swap_b32_e32 v83, v89
	v_cndmask_b32_e64 v89, v83, v89, s[6:7]
	v_mov_b32_e32 v83, v88
	v_mov_b32_e32 v90, v88
	s_nop 1
	v_permlane32_swap_b32_e32 v83, v90
	v_cndmask_b32_e64 v90, v83, v90, s[6:7]
	v_cndmask_b32_e64 v83, v85, 1.0, s[4:5]
	v_cndmask_b32_e64 v85, v86, 0, s[4:5]
	v_mul_f32_e32 v86, v83, v89
	v_cndmask_b32_e64 v86, v86, v83, s[6:7]
	v_fma_f32 v83, v83, v90, v85
	v_cndmask_b32_e64 v83, v83, v85, s[6:7]
	v_fmac_f32_e32 v83, v84, v86
	v_fmac_f32_e32 v15, v107, v83
	v_fmac_f32_e32 v80, v106, v15
	v_cvt_pk_bf16_f32 v83, v15, v15
	ds_write_b16 v61, v83 offset:48896
	v_cvt_pk_bf16_f32 v15, v80, v80
	v_fmac_f32_e32 v81, v105, v80
	v_lshlrev_b32_e32 v14, 1, v14
	v_mul_lo_u32 v13, v13, s67
	ds_write_b16 v61, v15 offset:49168
	v_cvt_pk_bf16_f32 v15, v81, v81
	v_fmac_f32_e32 v82, v104, v81
	v_add3_u32 v13, 0, v14, v13
	ds_write_b16 v61, v15 offset:49440
	v_cvt_pk_bf16_f32 v15, v82, v82
	ds_write_b16 v61, v15 offset:49712
	s_waitcnt lgkmcnt(0)
	s_barrier
	ds_read_b128 v[80:83], v13 offset:35840
	s_waitcnt vmcnt(1)
	v_lshlrev_b32_e32 v14, 16, v4
	v_and_b32_e32 v4, 0xffff0000, v4
	v_fma_f32 v85, v88, v89, v90
	v_fmac_f32_e32 v88, v87, v90
	s_waitcnt lgkmcnt(0)
	v_lshlrev_b32_e32 v15, 16, v80
	v_mul_f32_e32 v14, v15, v14
	v_and_b32_e32 v15, 0xffff0000, v80
	v_mul_f32_e32 v4, v15, v4
	v_cvt_pk_bf16_f32 v4, v14, v4
	v_lshlrev_b32_e32 v14, 16, v5
	v_lshlrev_b32_e32 v15, 16, v81
	v_mul_f32_e32 v14, v15, v14
	v_and_b32_e32 v15, 0xffff0000, v81
	v_and_b32_e32 v5, 0xffff0000, v5
	v_mul_f32_e32 v5, v15, v5
	v_cvt_pk_bf16_f32 v5, v14, v5
	v_lshlrev_b32_e32 v14, 16, v6
	v_lshlrev_b32_e32 v15, 16, v82
	v_mul_f32_e32 v14, v15, v14
	v_and_b32_e32 v15, 0xffff0000, v82
	v_and_b32_e32 v6, 0xffff0000, v6
	v_mul_f32_e32 v6, v15, v6
	v_cvt_pk_bf16_f32 v6, v14, v6
	v_lshlrev_b32_e32 v14, 16, v7
	v_lshlrev_b32_e32 v15, 16, v83
	v_mul_f32_e32 v14, v15, v14
	v_and_b32_e32 v15, 0xffff0000, v83
	v_and_b32_e32 v7, 0xffff0000, v7
	v_mul_f32_e32 v7, v15, v7
	v_cvt_pk_bf16_f32 v7, v14, v7
	ds_read_b128 v[80:83], v13 offset:44544
	v_lshl_add_u64 v[14:15], s[52:53], 0, v[66:67]
	v_lshl_add_u64 v[10:11], v[14:15], 0, v[10:11]
	global_store_dwordx4 v[10:11], v[4:7], off sc1
	v_mul_f32_e32 v86, v87, v89
	v_cndmask_b32_e64 v13, v88, v85, s[6:7]
	s_waitcnt vmcnt(1)
	v_lshlrev_b32_e32 v4, 16, v0
	s_waitcnt lgkmcnt(0)
	v_lshlrev_b32_e32 v5, 16, v80
	v_mul_f32_e32 v4, v5, v4
	v_and_b32_e32 v5, 0xffff0000, v80
	v_and_b32_e32 v0, 0xffff0000, v0
	v_mul_f32_e32 v0, v5, v0
	v_cvt_pk_bf16_f32 v0, v4, v0
	v_lshlrev_b32_e32 v4, 16, v1
	v_lshlrev_b32_e32 v5, 16, v81
	v_mul_f32_e32 v4, v5, v4
	v_and_b32_e32 v5, 0xffff0000, v81
	v_and_b32_e32 v1, 0xffff0000, v1
	v_mul_f32_e32 v1, v5, v1
	v_cvt_pk_bf16_f32 v1, v4, v1
	v_lshlrev_b32_e32 v4, 16, v2
	v_lshlrev_b32_e32 v5, 16, v82
	v_mul_f32_e32 v4, v5, v4
	v_and_b32_e32 v5, 0xffff0000, v82
	v_and_b32_e32 v2, 0xffff0000, v2
	v_lshlrev_b32_e32 v80, 16, v120
	v_mul_f32_e32 v2, v5, v2
	v_fmac_f32_e32 v13, v84, v86
	v_and_b32_e32 v81, 0xffff0000, v120
	v_add_f32_e32 v84, v217, v80
	v_cvt_pk_bf16_f32 v2, v4, v2
	v_lshlrev_b32_e32 v4, 16, v3
	v_lshlrev_b32_e32 v5, 16, v83
	v_lshlrev_b32_e32 v82, 16, v119
	v_fma_f32 v84, v116, v84, v81
	v_mul_f32_e32 v4, v5, v4
	v_and_b32_e32 v5, 0xffff0000, v83
	v_and_b32_e32 v83, 0xffff0000, v119
	v_fma_f32 v84, v115, v84, v82
	v_mov_b32_e32 v85, v118
	v_mov_b32_e32 v86, v118
	v_and_b32_e32 v3, 0xffff0000, v3
	v_fma_f32 v84, v114, v84, v83
	v_permlane16_swap_b32_e32 v85, v86
	v_mul_f32_e32 v3, v5, v3
	v_cndmask_b32_e64 v85, v85, v86, s[4:5]
	v_mov_b32_e32 v86, v84
	v_mov_b32_e32 v87, v84
	v_cvt_pk_bf16_f32 v3, v4, v3
	v_lshl_add_u64 v[4:5], v[14:15], 0, v[8:9]
	s_nop 0
	v_permlane16_swap_b32_e32 v86, v87
	global_store_dwordx4 v[4:5], v[0:3], off sc1
	v_cndmask_b32_e64 v86, v86, v87, s[4:5]
	s_nop 0
	v_mov_b32_e32 v0, v60
	s_barrier
	v_mul_f32_e32 v87, v118, v85
	v_lshlrev_b32_e32 v1, 3, v0
	v_ashrrev_i32_e32 v15, 4, v0
	v_fma_f32 v88, v84, v85, v86
	v_fmac_f32_e32 v84, v118, v86
	v_and_b32_e32 v14, 0x78, v1
	v_add_u32_e32 v0, s77, v15
	v_cndmask_b32_e64 v84, v84, v88, s[4:5]
	v_mov_b32_e32 v88, v87
	v_mov_b32_e32 v89, v87
	v_or_b32_e32 v1, s37, v14
	v_add_u32_e32 v0, 0xc0, v0
	v_permlane32_swap_b32_e32 v88, v89
	v_lshlrev_b32_e32 v66, 1, v1
	v_ashrrev_i32_e32 v1, 31, v0
	v_cndmask_b32_e64 v88, v88, v89, s[6:7]
	v_mov_b32_e32 v89, v84
	v_mov_b32_e32 v90, v84
	v_lshl_add_u64 v[2:3], s[38:39], 0, v[66:67]
	v_lshlrev_b64 v[10:11], 11, v[0:1]
	v_permlane32_swap_b32_e32 v89, v90
	v_cndmask_b32_e64 v85, v85, 1.0, s[4:5]
	v_lshl_add_u64 v[0:1], v[2:3], 0, v[10:11]
	v_cndmask_b32_e64 v89, v89, v90, s[6:7]
	v_cndmask_b32_e64 v86, v86, 0, s[4:5]
	v_mul_f32_e32 v91, v85, v88
	global_load_dwordx4 v[4:7], v[0:1], off nt
	v_cndmask_b32_e64 v91, v91, v85, s[6:7]
	v_fma_f32 v85, v85, v89, v86
	v_cndmask_b32_e64 v85, v85, v86, s[6:7]
	v_lshl_add_u64 v[8:9], v[10:11], 0, s[60:61]
	v_fmac_f32_e32 v85, v13, v91
	v_lshl_add_u64 v[0:1], v[2:3], 0, v[8:9]
	v_fmac_f32_e32 v80, v117, v85
	global_load_dwordx4 v[0:3], v[0:1], off nt
	v_cvt_pk_bf16_f32 v85, v80, v80
	ds_write_b16 v61, v85 offset:35840
	v_fmac_f32_e32 v81, v116, v80
	v_cvt_pk_bf16_f32 v80, v81, v81
	ds_write_b16 v61, v80 offset:36112
	v_fmac_f32_e32 v82, v115, v81
	v_cvt_pk_bf16_f32 v80, v82, v82
	v_fma_f32 v90, v84, v88, v89
	ds_write_b16 v61, v80 offset:36384
	v_fmac_f32_e32 v83, v114, v82
	v_cvt_pk_bf16_f32 v80, v83, v83
	v_fmac_f32_e32 v84, v87, v89
	ds_write_b16 v61, v80 offset:36656
	v_mul_f32_e32 v80, v87, v88
	v_cndmask_b32_e64 v81, v84, v90, s[6:7]
	v_fmac_f32_e32 v81, v13, v80
	v_lshlrev_b32_e32 v13, 16, v127
	v_and_b32_e32 v80, 0xffff0000, v127
	v_add_f32_e32 v84, v216, v13
	v_lshlrev_b32_e32 v82, 16, v126
	v_fma_f32 v84, v123, v84, v80
	v_and_b32_e32 v83, 0xffff0000, v126
	v_fma_f32 v84, v122, v84, v82
	v_mov_b32_e32 v85, v125
	v_mov_b32_e32 v86, v125
	v_fma_f32 v84, v121, v84, v83
	s_nop 0
	v_permlane16_swap_b32_e32 v85, v86
	v_cndmask_b32_e64 v85, v85, v86, s[4:5]
	v_mov_b32_e32 v86, v84
	v_mov_b32_e32 v87, v84
	s_nop 1
	v_permlane16_swap_b32_e32 v86, v87
	v_cndmask_b32_e64 v86, v86, v87, s[4:5]
	v_mul_f32_e32 v87, v125, v85
	v_fma_f32 v88, v84, v85, v86
	v_fmac_f32_e32 v84, v125, v86
	v_cndmask_b32_e64 v84, v84, v88, s[4:5]
	v_mov_b32_e32 v88, v87
	v_mov_b32_e32 v89, v87
	s_nop 1
	v_permlane32_swap_b32_e32 v88, v89
	v_cndmask_b32_e64 v88, v88, v89, s[6:7]
	v_mov_b32_e32 v89, v84
	v_mov_b32_e32 v90, v84
	s_nop 1
	v_permlane32_swap_b32_e32 v89, v90
	v_cndmask_b32_e64 v85, v85, 1.0, s[4:5]
	v_cndmask_b32_e64 v89, v89, v90, s[6:7]
	v_cndmask_b32_e64 v86, v86, 0, s[4:5]
	v_mul_f32_e32 v91, v85, v88
	v_cndmask_b32_e64 v91, v91, v85, s[6:7]
	v_fma_f32 v85, v85, v89, v86
	v_cndmask_b32_e64 v85, v85, v86, s[6:7]
	v_fmac_f32_e32 v85, v81, v91
	v_fmac_f32_e32 v13, v124, v85
	v_cvt_pk_bf16_f32 v85, v13, v13
	ds_write_b16 v61, v85 offset:40192
	v_fmac_f32_e32 v80, v123, v13
	v_cvt_pk_bf16_f32 v13, v80, v80
	ds_write_b16 v61, v13 offset:40464
	v_fmac_f32_e32 v82, v122, v80
	v_cvt_pk_bf16_f32 v13, v82, v82
	v_fma_f32 v90, v84, v88, v89
	ds_write_b16 v61, v13 offset:40736
	v_fmac_f32_e32 v83, v121, v82
	v_cvt_pk_bf16_f32 v13, v83, v83
	v_fmac_f32_e32 v84, v87, v89
	ds_write_b16 v61, v13 offset:41008
	v_mul_f32_e32 v13, v87, v88
	v_cndmask_b32_e64 v80, v84, v90, s[6:7]
	v_fmac_f32_e32 v80, v81, v13
	v_lshlrev_b32_e32 v13, 16, v138
	v_and_b32_e32 v81, 0xffff0000, v138
	v_add_f32_e32 v84, v214, v13
	v_lshlrev_b32_e32 v82, 16, v137
	v_fma_f32 v84, v130, v84, v81
	v_and_b32_e32 v83, 0xffff0000, v137
	v_fma_f32 v84, v129, v84, v82
	v_mov_b32_e32 v85, v136
	v_mov_b32_e32 v86, v136
	v_fma_f32 v84, v128, v84, v83
	s_nop 0
	v_permlane16_swap_b32_e32 v85, v86
	v_cndmask_b32_e64 v85, v85, v86, s[4:5]
	v_mov_b32_e32 v86, v84
	v_mov_b32_e32 v87, v84
	s_nop 1
	v_permlane16_swap_b32_e32 v86, v87
	v_cndmask_b32_e64 v86, v86, v87, s[4:5]
	v_mul_f32_e32 v87, v136, v85
	v_fma_f32 v88, v84, v85, v86
	v_fmac_f32_e32 v84, v136, v86
	v_cndmask_b32_e64 v84, v84, v88, s[4:5]
	v_mov_b32_e32 v88, v87
	v_mov_b32_e32 v89, v87
	s_nop 1
	v_permlane32_swap_b32_e32 v88, v89
	v_cndmask_b32_e64 v88, v88, v89, s[6:7]
	v_mov_b32_e32 v89, v84
	v_mov_b32_e32 v90, v84
	s_nop 1
	v_permlane32_swap_b32_e32 v89, v90
	v_cndmask_b32_e64 v85, v85, 1.0, s[4:5]
	v_cndmask_b32_e64 v89, v89, v90, s[6:7]
	v_cndmask_b32_e64 v86, v86, 0, s[4:5]
	v_mul_f32_e32 v91, v85, v88
	v_cndmask_b32_e64 v91, v91, v85, s[6:7]
	v_fma_f32 v85, v85, v89, v86
	v_cndmask_b32_e64 v85, v85, v86, s[6:7]
	v_fmac_f32_e32 v85, v80, v91
	v_fmac_f32_e32 v13, v131, v85
	v_cvt_pk_bf16_f32 v85, v13, v13
	ds_write_b16 v61, v85 offset:44544
	v_fmac_f32_e32 v81, v130, v13
	v_cvt_pk_bf16_f32 v13, v81, v81
	ds_write_b16 v61, v13 offset:44816
	v_fmac_f32_e32 v82, v129, v81
	v_cvt_pk_bf16_f32 v13, v82, v82
	v_fma_f32 v90, v84, v88, v89
	ds_write_b16 v61, v13 offset:45088
	v_fmac_f32_e32 v83, v128, v82
	v_cvt_pk_bf16_f32 v13, v83, v83
	v_fmac_f32_e32 v84, v87, v89
	ds_write_b16 v61, v13 offset:45360
	v_mul_f32_e32 v13, v87, v88
	v_cndmask_b32_e64 v81, v84, v90, s[6:7]
	v_fmac_f32_e32 v81, v80, v13
	v_lshlrev_b32_e32 v13, 16, v152
	v_and_b32_e32 v80, 0xffff0000, v152
	v_add_f32_e32 v84, v213, v13
	v_lshlrev_b32_e32 v82, 16, v150
	v_fma_f32 v84, v141, v84, v80
	v_and_b32_e32 v83, 0xffff0000, v150
	v_fma_f32 v84, v140, v84, v82
	v_mov_b32_e32 v85, v143
	v_mov_b32_e32 v86, v143
	v_fma_f32 v84, v139, v84, v83
	s_nop 0
	v_permlane16_swap_b32_e32 v85, v86
	v_cndmask_b32_e64 v85, v85, v86, s[4:5]
	v_mov_b32_e32 v86, v84
	v_mov_b32_e32 v87, v84
	s_nop 1
	v_permlane16_swap_b32_e32 v86, v87
	v_cndmask_b32_e64 v86, v86, v87, s[4:5]
	v_mul_f32_e32 v87, v143, v85
	v_fma_f32 v88, v84, v85, v86
	v_fmac_f32_e32 v84, v143, v86
	v_cndmask_b32_e64 v84, v84, v88, s[4:5]
	v_mov_b32_e32 v88, v87
	s_nop 1
	v_permlane32_swap_b32_e32 v87, v88
	v_cndmask_b32_e64 v87, v87, v88, s[6:7]
	v_mov_b32_e32 v88, v84
	s_nop 1
	v_permlane32_swap_b32_e32 v84, v88
	v_cndmask_b32_e64 v84, v84, v88, s[6:7]
	v_cndmask_b32_e64 v85, v85, 1.0, s[4:5]
	v_cndmask_b32_e64 v86, v86, 0, s[4:5]
	v_mul_f32_e32 v87, v85, v87
	v_fma_f32 v84, v85, v84, v86
	v_cndmask_b32_e64 v87, v87, v85, s[6:7]
	v_cndmask_b32_e64 v84, v84, v86, s[6:7]
	v_fmac_f32_e32 v84, v81, v87
	v_fmac_f32_e32 v13, v142, v84
	v_cvt_pk_bf16_f32 v81, v13, v13
	ds_write_b16 v61, v81 offset:48896
	v_fmac_f32_e32 v80, v141, v13
	v_cvt_pk_bf16_f32 v13, v80, v80
	ds_write_b16 v61, v13 offset:49168
	v_fmac_f32_e32 v82, v140, v80
	v_cvt_pk_bf16_f32 v13, v82, v82
	ds_write_b16 v61, v13 offset:49440
	v_fmac_f32_e32 v83, v139, v82
	v_cvt_pk_bf16_f32 v13, v83, v83
	ds_write_b16 v61, v13 offset:49712
	v_lshlrev_b32_e32 v13, 1, v14
	v_mul_lo_u32 v14, v15, s67
	v_add3_u32 v13, 0, v13, v14
	s_waitcnt lgkmcnt(0)
	s_barrier
	ds_read_b128 v[80:83], v13 offset:35840
	s_waitcnt vmcnt(1)
	v_lshlrev_b32_e32 v14, 16, v4
	v_and_b32_e32 v4, 0xffff0000, v4
	v_fmac_f32_e32 v79, v78, v12
	s_cmp_lg_u32 s75, 4
	s_waitcnt lgkmcnt(0)
	v_lshlrev_b32_e32 v15, 16, v80
	v_mul_f32_e32 v14, v15, v14
	v_and_b32_e32 v15, 0xffff0000, v80
	v_mul_f32_e32 v4, v15, v4
	v_cvt_pk_bf16_f32 v4, v14, v4
	v_lshlrev_b32_e32 v14, 16, v5
	v_lshlrev_b32_e32 v15, 16, v81
	v_mul_f32_e32 v14, v15, v14
	v_and_b32_e32 v15, 0xffff0000, v81
	v_and_b32_e32 v5, 0xffff0000, v5
	v_mul_f32_e32 v5, v15, v5
	v_cvt_pk_bf16_f32 v5, v14, v5
	v_lshlrev_b32_e32 v14, 16, v6
	v_lshlrev_b32_e32 v15, 16, v82
	v_mul_f32_e32 v14, v15, v14
	v_and_b32_e32 v15, 0xffff0000, v82
	v_and_b32_e32 v6, 0xffff0000, v6
	v_mul_f32_e32 v6, v15, v6
	v_cvt_pk_bf16_f32 v6, v14, v6
	v_lshlrev_b32_e32 v14, 16, v7
	v_lshlrev_b32_e32 v15, 16, v83
	v_mul_f32_e32 v14, v15, v14
	v_and_b32_e32 v15, 0xffff0000, v83
	v_and_b32_e32 v7, 0xffff0000, v7
	v_mul_f32_e32 v7, v15, v7
	v_cvt_pk_bf16_f32 v7, v14, v7
	ds_read_b128 v[80:83], v13 offset:44544
	v_lshl_add_u64 v[14:15], s[52:53], 0, v[66:67]
	v_lshl_add_u64 v[10:11], v[14:15], 0, v[10:11]
	global_store_dwordx4 v[10:11], v[4:7], off sc1
	v_mov_b32_e32 v113, v79
	s_waitcnt vmcnt(1)
	v_lshlrev_b32_e32 v4, 16, v0
	s_waitcnt lgkmcnt(0)
	v_lshlrev_b32_e32 v5, 16, v80
	v_mul_f32_e32 v4, v5, v4
	v_and_b32_e32 v5, 0xffff0000, v80
	v_and_b32_e32 v0, 0xffff0000, v0
	v_mul_f32_e32 v0, v5, v0
	v_cvt_pk_bf16_f32 v0, v4, v0
	v_lshlrev_b32_e32 v4, 16, v1
	v_lshlrev_b32_e32 v5, 16, v81
	v_mul_f32_e32 v4, v5, v4
	v_and_b32_e32 v5, 0xffff0000, v81
	v_and_b32_e32 v1, 0xffff0000, v1
	v_mul_f32_e32 v1, v5, v1
	v_cvt_pk_bf16_f32 v1, v4, v1
	v_lshlrev_b32_e32 v4, 16, v2
	v_lshlrev_b32_e32 v5, 16, v82
	v_mul_f32_e32 v4, v5, v4
	v_and_b32_e32 v5, 0xffff0000, v82
	v_and_b32_e32 v2, 0xffff0000, v2
	v_mul_f32_e32 v2, v5, v2
	v_cvt_pk_bf16_f32 v2, v4, v2
	v_lshlrev_b32_e32 v4, 16, v3
	v_lshlrev_b32_e32 v5, 16, v83
	v_mul_f32_e32 v4, v5, v4
	v_and_b32_e32 v5, 0xffff0000, v83
	v_and_b32_e32 v3, 0xffff0000, v3
	v_mul_f32_e32 v3, v5, v3
	v_cvt_pk_bf16_f32 v3, v4, v3
	v_lshl_add_u64 v[4:5], v[14:15], 0, v[8:9]
	global_store_dwordx4 v[4:5], v[0:3], off sc1
	s_barrier
	s_cbranch_scc0 .LBB0_610
